# K-loops: LDS-DMA group issued before the fragment ds_reads in every load segment
# baseline (speedup 1.0000x reference)
.LBB0_178:
	s_add_u32 s54, s52, 0xfffc0080
	s_addc_u32 s55, s53, -1
	s_cmp_eq_u32 s87, 12
	s_cselect_b32 s57, s5, s55
	s_cselect_b32 s56, s10, s54
	s_cselect_b32 s55, s11, s86
	s_cselect_b32 s54, s39, s41
	v_lshl_add_u64 v[166:167], s[52:53], 0, v[140:141]
	s_add_i32 m0, s49, 0xc000
	s_nop 0
	global_load_lds_dwordx4 v[166:167], off
	v_lshl_add_u64 v[166:167], s[52:53], 0, v[142:143]
	s_add_i32 m0, s49, 0xe000
	s_nop 0
	global_load_lds_dwordx4 v[166:167], off
	ds_read_b128 v[148:151], v171
	ds_read_b128 v[152:155], v171 offset:1024
	ds_read_b128 v[156:159], v171 offset:2048
	ds_read_b128 v[160:163], v171 offset:3072
	ds_read_b128 v[190:193], v173
	ds_read_b128 v[198:201], v173 offset:1024
	ds_read_b128 v[202:205], v173 offset:2048
	ds_read_b128 v[206:209], v173 offset:3072
	ds_read_b128 v[210:213], v177
	ds_read_b128 v[214:217], v177 offset:1024
	ds_read_b128 v[218:221], v177 offset:2048
	ds_read_b128 v[222:225], v177 offset:3072
	ds_read_b128 v[226:229], v177 offset:4096
	ds_read_b128 v[230:233], v177 offset:5120
	ds_read_b128 v[234:237], v177 offset:6144
	ds_read_b128 v[238:241], v177 offset:7168
	s_waitcnt vmcnt(8)
	s_waitcnt lgkmcnt(0)
	s_barrier
	s_setprio 1
	s_waitcnt lgkmcnt(0)
	v_mfma_f32_16x16x32_bf16 v[124:127], v[148:151], v[210:213], v[124:127]
	v_mfma_f32_16x16x32_bf16 v[120:123], v[156:159], v[210:213], v[120:123]
	v_mfma_f32_16x16x32_bf16 v[108:111], v[148:151], v[218:221], v[108:111]
	v_mfma_f32_16x16x32_bf16 v[104:107], v[156:159], v[218:221], v[104:107]
	v_mfma_f32_16x16x32_bf16 v[92:95], v[148:151], v[226:229], v[92:95]
	v_mfma_f32_16x16x32_bf16 v[88:91], v[156:159], v[226:229], v[88:91]
	v_mfma_f32_16x16x32_bf16 v[76:79], v[148:151], v[234:237], v[76:79]
	v_mfma_f32_16x16x32_bf16 v[72:75], v[156:159], v[234:237], v[72:75]
	v_mfma_f32_16x16x32_bf16 v[124:127], v[152:155], v[214:217], v[124:127]
	v_mfma_f32_16x16x32_bf16 v[120:123], v[160:163], v[214:217], v[120:123]
	v_mfma_f32_16x16x32_bf16 v[108:111], v[152:155], v[222:225], v[108:111]
	v_mfma_f32_16x16x32_bf16 v[104:107], v[160:163], v[222:225], v[104:107]
	v_mfma_f32_16x16x32_bf16 v[92:95], v[152:155], v[230:233], v[92:95]
	v_mfma_f32_16x16x32_bf16 v[88:91], v[160:163], v[230:233], v[88:91]
	v_mfma_f32_16x16x32_bf16 v[76:79], v[152:155], v[238:241], v[76:79]
	v_mfma_f32_16x16x32_bf16 v[72:75], v[160:163], v[238:241], v[72:75]
	s_setprio 0
	s_setprio 1
	v_mfma_f32_16x16x32_bf16 v[116:119], v[190:193], v[210:213], v[116:119]
	v_mfma_f32_16x16x32_bf16 v[112:115], v[202:205], v[210:213], v[112:115]
	v_mfma_f32_16x16x32_bf16 v[100:103], v[190:193], v[218:221], v[100:103]
	v_mfma_f32_16x16x32_bf16 v[96:99], v[202:205], v[218:221], v[96:99]
	v_mfma_f32_16x16x32_bf16 v[84:87], v[190:193], v[226:229], v[84:87]
	v_mfma_f32_16x16x32_bf16 v[80:83], v[202:205], v[226:229], v[80:83]
	v_mfma_f32_16x16x32_bf16 v[68:71], v[190:193], v[234:237], v[68:71]
	v_mfma_f32_16x16x32_bf16 v[64:67], v[202:205], v[234:237], v[64:67]
	v_mfma_f32_16x16x32_bf16 v[116:119], v[198:201], v[214:217], v[116:119]
	v_mfma_f32_16x16x32_bf16 v[112:115], v[206:209], v[214:217], v[112:115]
	v_mfma_f32_16x16x32_bf16 v[100:103], v[198:201], v[222:225], v[100:103]
	v_mfma_f32_16x16x32_bf16 v[96:99], v[206:209], v[222:225], v[96:99]
	v_mfma_f32_16x16x32_bf16 v[84:87], v[198:201], v[230:233], v[84:87]
	v_mfma_f32_16x16x32_bf16 v[80:83], v[206:209], v[230:233], v[80:83]
	v_mfma_f32_16x16x32_bf16 v[68:71], v[198:201], v[238:241], v[68:71]
	v_mfma_f32_16x16x32_bf16 v[64:67], v[206:209], v[238:241], v[64:67]
	s_setprio 0
	s_barrier
	s_add_i32 s88, s81, s64
	v_lshl_add_u64 v[166:167], s[54:55], 0, v[130:131]
	s_mov_b32 m0, s88
	s_nop 0
	global_load_lds_dwordx4 v[166:167], off
	s_add_i32 m0, s88, 0x2000
	s_add_u32 s90, s54, 0x40000
	v_lshl_add_u64 v[174:175], s[54:55], 0, v[134:135]
	s_addc_u32 s91, s55, 0
	s_add_i32 s88, s82, s64
	global_load_lds_dwordx4 v[174:175], off
	v_lshl_add_u64 v[178:179], s[90:91], 0, v[130:131]
	s_mov_b32 m0, s88
	v_lshl_add_u64 v[182:183], s[56:57], 0, v[132:133]
	global_load_lds_dwordx4 v[178:179], off
	v_lshl_add_u64 v[178:179], s[90:91], 0, v[134:135]
	s_add_i32 m0, s88, 0x2000
	s_nop 0
	global_load_lds_dwordx4 v[178:179], off
	v_lshl_add_u64 v[178:179], s[56:57], 0, v[128:129]
	s_mov_b32 m0, s49
	s_nop 0
	global_load_lds_dwordx4 v[178:179], off
	s_mov_b32 m0, s65
	s_nop 0
	global_load_lds_dwordx4 v[182:183], off
	ds_read_b128 v[210:213], v177 offset:16384
	ds_read_b128 v[214:217], v177 offset:17408
	ds_read_b128 v[218:221], v177 offset:18432
	ds_read_b128 v[222:225], v177 offset:19456
	ds_read_b128 v[226:229], v177 offset:20480
	ds_read_b128 v[230:233], v177 offset:21504
	ds_read_b128 v[234:237], v177 offset:22528
	ds_read_b128 v[238:241], v177 offset:23552
	s_waitcnt vmcnt(8)
	s_waitcnt lgkmcnt(0)
	s_barrier
	s_setprio 1
	s_waitcnt lgkmcnt(0)
	v_mfma_f32_16x16x32_bf16 v[60:63], v[148:151], v[210:213], v[60:63]
	v_mfma_f32_16x16x32_bf16 v[56:59], v[156:159], v[210:213], v[56:59]
	v_mfma_f32_16x16x32_bf16 v[44:47], v[148:151], v[218:221], v[44:47]
	v_mfma_f32_16x16x32_bf16 v[40:43], v[156:159], v[218:221], v[40:43]
	v_mfma_f32_16x16x32_bf16 v[28:31], v[148:151], v[226:229], v[28:31]
	v_mfma_f32_16x16x32_bf16 v[24:27], v[156:159], v[226:229], v[24:27]
	v_mfma_f32_16x16x32_bf16 v[12:15], v[148:151], v[234:237], v[12:15]
	v_mfma_f32_16x16x32_bf16 v[8:11], v[156:159], v[234:237], v[8:11]
	v_mfma_f32_16x16x32_bf16 v[60:63], v[152:155], v[214:217], v[60:63]
	v_mfma_f32_16x16x32_bf16 v[56:59], v[160:163], v[214:217], v[56:59]
	v_mfma_f32_16x16x32_bf16 v[44:47], v[152:155], v[222:225], v[44:47]
	v_mfma_f32_16x16x32_bf16 v[40:43], v[160:163], v[222:225], v[40:43]
	v_mfma_f32_16x16x32_bf16 v[28:31], v[152:155], v[230:233], v[28:31]
	v_mfma_f32_16x16x32_bf16 v[24:27], v[160:163], v[230:233], v[24:27]
	v_mfma_f32_16x16x32_bf16 v[12:15], v[152:155], v[238:241], v[12:15]
	v_mfma_f32_16x16x32_bf16 v[8:11], v[160:163], v[238:241], v[8:11]
	s_setprio 0
	s_setprio 1
	v_mfma_f32_16x16x32_bf16 v[52:55], v[190:193], v[210:213], v[52:55]
	v_mfma_f32_16x16x32_bf16 v[48:51], v[202:205], v[210:213], v[48:51]
	v_mfma_f32_16x16x32_bf16 v[36:39], v[190:193], v[218:221], v[36:39]
	v_mfma_f32_16x16x32_bf16 v[32:35], v[202:205], v[218:221], v[32:35]
	v_mfma_f32_16x16x32_bf16 v[20:23], v[190:193], v[226:229], v[20:23]
	v_mfma_f32_16x16x32_bf16 v[16:19], v[202:205], v[226:229], v[16:19]
	v_mfma_f32_16x16x32_bf16 v[4:7], v[190:193], v[234:237], v[4:7]
	v_mfma_f32_16x16x32_bf16 v[0:3], v[202:205], v[234:237], v[0:3]
	v_mfma_f32_16x16x32_bf16 v[52:55], v[198:201], v[214:217], v[52:55]
	v_mfma_f32_16x16x32_bf16 v[48:51], v[206:209], v[214:217], v[48:51]
	v_mfma_f32_16x16x32_bf16 v[36:39], v[198:201], v[222:225], v[36:39]
	v_mfma_f32_16x16x32_bf16 v[32:35], v[206:209], v[222:225], v[32:35]
	v_mfma_f32_16x16x32_bf16 v[20:23], v[198:201], v[230:233], v[20:23]
	v_mfma_f32_16x16x32_bf16 v[16:19], v[206:209], v[230:233], v[16:19]
	v_mfma_f32_16x16x32_bf16 v[4:7], v[198:201], v[238:241], v[4:7]
	v_mfma_f32_16x16x32_bf16 v[0:3], v[206:209], v[238:241], v[0:3]
	s_setprio 0
	s_barrier
	s_add_i32 s88, 0, 0x18000
	s_add_i32 s90, 0, 0x1c000
	s_add_u32 s56, s56, 0x40000
	s_addc_u32 s57, s57, 0
	s_mov_b32 m0, s66
	v_lshl_add_u64 v[186:187], s[56:57], 0, v[128:129]
	global_load_lds_dwordx4 v[186:187], off
	v_lshl_add_u64 v[186:187], s[56:57], 0, v[132:133]
	s_mov_b32 m0, s67
	s_nop 0
	global_load_lds_dwordx4 v[186:187], off
	v_add_u32_e32 v136, s88, v169
	ds_read_b128 v[148:151], v136
	ds_read_b128 v[152:155], v136 offset:1024
	ds_read_b128 v[156:159], v136 offset:2048
	ds_read_b128 v[160:163], v136 offset:3072
	v_add_u32_e32 v136, s90, v169
	ds_read_b128 v[190:193], v136
	ds_read_b128 v[198:201], v136 offset:1024
	ds_read_b128 v[202:205], v136 offset:2048
	ds_read_b128 v[206:209], v136 offset:3072
	ds_read_b128 v[210:213], v177 offset:32768
	ds_read_b128 v[214:217], v177 offset:33792
	ds_read_b128 v[218:221], v177 offset:34816
	ds_read_b128 v[222:225], v177 offset:35840
	ds_read_b128 v[226:229], v177 offset:36864
	ds_read_b128 v[230:233], v177 offset:37888
	ds_read_b128 v[234:237], v177 offset:38912
	ds_read_b128 v[238:241], v177 offset:39936
	s_waitcnt vmcnt(8)
	s_waitcnt lgkmcnt(0)
	s_barrier
	s_setprio 1
	s_waitcnt lgkmcnt(0)
	v_mfma_f32_16x16x32_bf16 v[124:127], v[148:151], v[210:213], v[124:127]
	v_mfma_f32_16x16x32_bf16 v[120:123], v[156:159], v[210:213], v[120:123]
	v_mfma_f32_16x16x32_bf16 v[108:111], v[148:151], v[218:221], v[108:111]
	v_mfma_f32_16x16x32_bf16 v[104:107], v[156:159], v[218:221], v[104:107]
	v_mfma_f32_16x16x32_bf16 v[92:95], v[148:151], v[226:229], v[92:95]
	v_mfma_f32_16x16x32_bf16 v[88:91], v[156:159], v[226:229], v[88:91]
	v_mfma_f32_16x16x32_bf16 v[76:79], v[148:151], v[234:237], v[76:79]
	v_mfma_f32_16x16x32_bf16 v[72:75], v[156:159], v[234:237], v[72:75]
	v_mfma_f32_16x16x32_bf16 v[124:127], v[152:155], v[214:217], v[124:127]
	v_mfma_f32_16x16x32_bf16 v[120:123], v[160:163], v[214:217], v[120:123]
	v_mfma_f32_16x16x32_bf16 v[108:111], v[152:155], v[222:225], v[108:111]
	v_mfma_f32_16x16x32_bf16 v[104:107], v[160:163], v[222:225], v[104:107]
	v_mfma_f32_16x16x32_bf16 v[92:95], v[152:155], v[230:233], v[92:95]
	v_mfma_f32_16x16x32_bf16 v[88:91], v[160:163], v[230:233], v[88:91]
	v_mfma_f32_16x16x32_bf16 v[76:79], v[152:155], v[238:241], v[76:79]
	v_mfma_f32_16x16x32_bf16 v[72:75], v[160:163], v[238:241], v[72:75]
	s_setprio 0
	s_setprio 1
	v_mfma_f32_16x16x32_bf16 v[116:119], v[190:193], v[210:213], v[116:119]
	v_mfma_f32_16x16x32_bf16 v[112:115], v[202:205], v[210:213], v[112:115]
	v_mfma_f32_16x16x32_bf16 v[100:103], v[190:193], v[218:221], v[100:103]
	v_mfma_f32_16x16x32_bf16 v[96:99], v[202:205], v[218:221], v[96:99]
	v_mfma_f32_16x16x32_bf16 v[84:87], v[190:193], v[226:229], v[84:87]
	v_mfma_f32_16x16x32_bf16 v[80:83], v[202:205], v[226:229], v[80:83]
	v_mfma_f32_16x16x32_bf16 v[68:71], v[190:193], v[234:237], v[68:71]
	v_mfma_f32_16x16x32_bf16 v[64:67], v[202:205], v[234:237], v[64:67]
	v_mfma_f32_16x16x32_bf16 v[116:119], v[198:201], v[214:217], v[116:119]
	v_mfma_f32_16x16x32_bf16 v[112:115], v[206:209], v[214:217], v[112:115]
	v_mfma_f32_16x16x32_bf16 v[100:103], v[198:201], v[222:225], v[100:103]
	v_mfma_f32_16x16x32_bf16 v[96:99], v[206:209], v[222:225], v[96:99]
	v_mfma_f32_16x16x32_bf16 v[84:87], v[198:201], v[230:233], v[84:87]
	v_mfma_f32_16x16x32_bf16 v[80:83], v[206:209], v[230:233], v[80:83]
	v_mfma_f32_16x16x32_bf16 v[68:71], v[198:201], v[238:241], v[68:71]
	v_mfma_f32_16x16x32_bf16 v[64:67], v[206:209], v[238:241], v[64:67]
	s_setprio 0
	s_barrier
	s_add_i32 s56, s88, s64
	v_lshl_add_u64 v[166:167], v[166:167], 0, s[14:15]
	s_mov_b32 m0, s56
	s_nop 0
	global_load_lds_dwordx4 v[166:167], off
	s_add_i32 m0, s56, 0x2000
	s_add_u32 s54, s54, 0x40080
	v_lshl_add_u64 v[166:167], v[174:175], 0, s[14:15]
	s_addc_u32 s55, s55, 0
	s_add_i32 s56, s90, s64
	global_load_lds_dwordx4 v[166:167], off
	v_lshl_add_u64 v[166:167], s[54:55], 0, v[130:131]
	s_mov_b32 m0, s56
	s_nop 0
	global_load_lds_dwordx4 v[166:167], off
	v_lshl_add_u64 v[166:167], s[54:55], 0, v[134:135]
	s_add_i32 m0, s56, 0x2000
	s_nop 0
	global_load_lds_dwordx4 v[166:167], off
	v_lshl_add_u64 v[166:167], v[178:179], 0, s[14:15]
	s_mov_b32 m0, s76
	s_nop 0
	global_load_lds_dwordx4 v[166:167], off
	v_lshl_add_u64 v[166:167], v[182:183], 0, s[14:15]
	s_mov_b32 m0, s77
	s_nop 0
	global_load_lds_dwordx4 v[166:167], off
	ds_read_b128 v[210:213], v177 offset:49152
	ds_read_b128 v[214:217], v177 offset:50176
	ds_read_b128 v[218:221], v177 offset:51200
	ds_read_b128 v[222:225], v177 offset:52224
	ds_read_b128 v[226:229], v177 offset:53248
	ds_read_b128 v[230:233], v177 offset:54272
	ds_read_b128 v[234:237], v177 offset:55296
	ds_read_b128 v[238:241], v177 offset:56320
	s_waitcnt vmcnt(8)
	s_waitcnt lgkmcnt(0)
	s_barrier
	s_setprio 1
	s_waitcnt lgkmcnt(0)
	v_mfma_f32_16x16x32_bf16 v[60:63], v[148:151], v[210:213], v[60:63]
	v_mfma_f32_16x16x32_bf16 v[56:59], v[156:159], v[210:213], v[56:59]
	v_mfma_f32_16x16x32_bf16 v[44:47], v[148:151], v[218:221], v[44:47]
	v_mfma_f32_16x16x32_bf16 v[40:43], v[156:159], v[218:221], v[40:43]
	v_mfma_f32_16x16x32_bf16 v[28:31], v[148:151], v[226:229], v[28:31]
	v_mfma_f32_16x16x32_bf16 v[24:27], v[156:159], v[226:229], v[24:27]
	v_mfma_f32_16x16x32_bf16 v[12:15], v[148:151], v[234:237], v[12:15]
	v_mfma_f32_16x16x32_bf16 v[8:11], v[156:159], v[234:237], v[8:11]
	v_mfma_f32_16x16x32_bf16 v[60:63], v[152:155], v[214:217], v[60:63]
	v_mfma_f32_16x16x32_bf16 v[56:59], v[160:163], v[214:217], v[56:59]
	v_mfma_f32_16x16x32_bf16 v[44:47], v[152:155], v[222:225], v[44:47]
	v_mfma_f32_16x16x32_bf16 v[40:43], v[160:163], v[222:225], v[40:43]
	v_mfma_f32_16x16x32_bf16 v[28:31], v[152:155], v[230:233], v[28:31]
	v_mfma_f32_16x16x32_bf16 v[24:27], v[160:163], v[230:233], v[24:27]
	v_mfma_f32_16x16x32_bf16 v[12:15], v[152:155], v[238:241], v[12:15]
	v_mfma_f32_16x16x32_bf16 v[8:11], v[160:163], v[238:241], v[8:11]
	s_setprio 0
	s_setprio 1
	v_mfma_f32_16x16x32_bf16 v[52:55], v[190:193], v[210:213], v[52:55]
	v_mfma_f32_16x16x32_bf16 v[48:51], v[202:205], v[210:213], v[48:51]
	v_mfma_f32_16x16x32_bf16 v[36:39], v[190:193], v[218:221], v[36:39]
	v_mfma_f32_16x16x32_bf16 v[32:35], v[202:205], v[218:221], v[32:35]
	v_mfma_f32_16x16x32_bf16 v[20:23], v[190:193], v[226:229], v[20:23]
	v_mfma_f32_16x16x32_bf16 v[16:19], v[202:205], v[226:229], v[16:19]
	v_mfma_f32_16x16x32_bf16 v[4:7], v[190:193], v[234:237], v[4:7]
	v_mfma_f32_16x16x32_bf16 v[0:3], v[202:205], v[234:237], v[0:3]
	v_mfma_f32_16x16x32_bf16 v[52:55], v[198:201], v[214:217], v[52:55]
	v_mfma_f32_16x16x32_bf16 v[48:51], v[206:209], v[214:217], v[48:51]
	v_mfma_f32_16x16x32_bf16 v[36:39], v[198:201], v[222:225], v[36:39]
	v_mfma_f32_16x16x32_bf16 v[32:35], v[206:209], v[222:225], v[32:35]
	v_mfma_f32_16x16x32_bf16 v[20:23], v[198:201], v[230:233], v[20:23]
	v_mfma_f32_16x16x32_bf16 v[16:19], v[206:209], v[230:233], v[16:19]
	v_mfma_f32_16x16x32_bf16 v[4:7], v[198:201], v[238:241], v[4:7]
	v_mfma_f32_16x16x32_bf16 v[0:3], v[206:209], v[238:241], v[0:3]
	s_setprio 0
	s_barrier
	s_add_i32 s87, s87, 2
	s_add_u32 s52, s52, 0x100
	s_addc_u32 s53, s53, 0
	s_add_u32 s41, s41, 0x100
	s_addc_u32 s86, s86, 0
	s_cmp_gt_u32 s87, 13
	s_cbranch_scc0 .LBB0_178
	s_and_b64 vcc, exec, s[16:17]
	s_cbranch_vccz .LBB0_181
	s_barrier

.LBB0_492:
	s_add_u32 s46, s44, 0xfffc0080
	s_addc_u32 s47, s45, -1
	s_cmp_eq_u32 s72, 12
	s_cselect_b32 s49, s10, s47
	s_cselect_b32 s48, s11, s46
	s_cselect_b32 s47, s35, s67
	s_cselect_b32 s46, s37, s43
	v_lshl_add_u64 v[210:211], s[44:45], 0, v[192:193]
	s_add_i32 m0, s54, 0xc000
	s_nop 0
	global_load_lds_dwordx4 v[210:211], off
	v_lshl_add_u64 v[210:211], s[44:45], 0, v[194:195]
	s_add_i32 m0, s54, 0xe000
	s_nop 0
	global_load_lds_dwordx4 v[210:211], off
	ds_read_b128 v[96:99], v222
	ds_read_b128 v[108:111], v222 offset:1024
	ds_read_b128 v[120:123], v222 offset:2048
	ds_read_b128 v[128:131], v222 offset:3072
	ds_read_b128 v[144:147], v223
	ds_read_b128 v[148:151], v223 offset:1024
	ds_read_b128 v[152:155], v223 offset:2048
	ds_read_b128 v[156:159], v223 offset:3072
	ds_read_b128 v[160:163], v224
	ds_read_b128 v[164:167], v224 offset:1024
	ds_read_b128 v[168:171], v224 offset:2048
	ds_read_b128 v[172:175], v224 offset:3072
	ds_read_b128 v[176:179], v224 offset:4096
	ds_read_b128 v[180:183], v224 offset:5120
	ds_read_b128 v[202:205], v224 offset:6144
	ds_read_b128 v[206:209], v224 offset:7168
	s_waitcnt vmcnt(8)
	s_waitcnt lgkmcnt(0)
	s_barrier
	s_setprio 1
	s_waitcnt lgkmcnt(0)
	v_mfma_f32_16x16x32_bf16 v[140:143], v[96:99], v[160:163], v[140:143]
	v_mfma_f32_16x16x32_bf16 v[136:139], v[120:123], v[160:163], v[136:139]
	v_mfma_f32_16x16x32_bf16 v[116:119], v[96:99], v[168:171], v[116:119]
	v_mfma_f32_16x16x32_bf16 v[112:115], v[120:123], v[168:171], v[112:115]
	v_mfma_f32_16x16x32_bf16 v[92:95], v[96:99], v[176:179], v[92:95]
	v_mfma_f32_16x16x32_bf16 v[88:91], v[120:123], v[176:179], v[88:91]
	v_mfma_f32_16x16x32_bf16 v[76:79], v[96:99], v[202:205], v[76:79]
	v_mfma_f32_16x16x32_bf16 v[72:75], v[120:123], v[202:205], v[72:75]
	v_mfma_f32_16x16x32_bf16 v[140:143], v[108:111], v[164:167], v[140:143]
	v_mfma_f32_16x16x32_bf16 v[136:139], v[128:131], v[164:167], v[136:139]
	v_mfma_f32_16x16x32_bf16 v[116:119], v[108:111], v[172:175], v[116:119]
	v_mfma_f32_16x16x32_bf16 v[112:115], v[128:131], v[172:175], v[112:115]
	v_mfma_f32_16x16x32_bf16 v[92:95], v[108:111], v[180:183], v[92:95]
	v_mfma_f32_16x16x32_bf16 v[88:91], v[128:131], v[180:183], v[88:91]
	v_mfma_f32_16x16x32_bf16 v[76:79], v[108:111], v[206:209], v[76:79]
	v_mfma_f32_16x16x32_bf16 v[72:75], v[128:131], v[206:209], v[72:75]
	s_setprio 0
	s_setprio 1
	v_mfma_f32_16x16x32_bf16 v[132:135], v[144:147], v[160:163], v[132:135]
	v_mfma_f32_16x16x32_bf16 v[124:127], v[152:155], v[160:163], v[124:127]
	v_mfma_f32_16x16x32_bf16 v[104:107], v[144:147], v[168:171], v[104:107]
	v_mfma_f32_16x16x32_bf16 v[100:103], v[152:155], v[168:171], v[100:103]
	v_mfma_f32_16x16x32_bf16 v[84:87], v[144:147], v[176:179], v[84:87]
	v_mfma_f32_16x16x32_bf16 v[80:83], v[152:155], v[176:179], v[80:83]
	v_mfma_f32_16x16x32_bf16 v[68:71], v[144:147], v[202:205], v[68:71]
	v_mfma_f32_16x16x32_bf16 v[64:67], v[152:155], v[202:205], v[64:67]
	v_mfma_f32_16x16x32_bf16 v[132:135], v[148:151], v[164:167], v[132:135]
	v_mfma_f32_16x16x32_bf16 v[124:127], v[156:159], v[164:167], v[124:127]
	v_mfma_f32_16x16x32_bf16 v[104:107], v[148:151], v[172:175], v[104:107]
	v_mfma_f32_16x16x32_bf16 v[100:103], v[156:159], v[172:175], v[100:103]
	v_mfma_f32_16x16x32_bf16 v[84:87], v[148:151], v[180:183], v[84:87]
	v_mfma_f32_16x16x32_bf16 v[80:83], v[156:159], v[180:183], v[80:83]
	v_mfma_f32_16x16x32_bf16 v[68:71], v[148:151], v[206:209], v[68:71]
	v_mfma_f32_16x16x32_bf16 v[64:67], v[156:159], v[206:209], v[64:67]
	s_setprio 0
	s_barrier
	s_add_i32 s73, s64, s53
	v_lshl_add_u64 v[210:211], s[46:47], 0, v[186:187]
	s_mov_b32 m0, s73
	s_nop 0
	global_load_lds_dwordx4 v[210:211], off
	s_add_i32 m0, s73, 0x2000
	s_add_u32 s74, s46, 0x40000
	v_lshl_add_u64 v[212:213], s[46:47], 0, v[190:191]
	s_addc_u32 s75, s47, 0
	s_add_i32 s73, s65, s53
	global_load_lds_dwordx4 v[212:213], off
	v_lshl_add_u64 v[214:215], s[74:75], 0, v[186:187]
	s_mov_b32 m0, s73
	v_lshl_add_u64 v[216:217], s[48:49], 0, v[188:189]
	global_load_lds_dwordx4 v[214:215], off
	v_lshl_add_u64 v[214:215], s[74:75], 0, v[190:191]
	s_add_i32 m0, s73, 0x2000
	s_nop 0
	global_load_lds_dwordx4 v[214:215], off
	v_lshl_add_u64 v[214:215], s[48:49], 0, v[184:185]
	s_mov_b32 m0, s54
	s_nop 0
	global_load_lds_dwordx4 v[214:215], off
	s_mov_b32 m0, s55
	s_nop 0
	global_load_lds_dwordx4 v[216:217], off
	ds_read_b128 v[160:163], v224 offset:16384
	ds_read_b128 v[164:167], v224 offset:17408
	ds_read_b128 v[168:171], v224 offset:18432
	ds_read_b128 v[172:175], v224 offset:19456
	ds_read_b128 v[176:179], v224 offset:20480
	ds_read_b128 v[180:183], v224 offset:21504
	ds_read_b128 v[202:205], v224 offset:22528
	ds_read_b128 v[206:209], v224 offset:23552
	s_waitcnt vmcnt(8)
	s_waitcnt lgkmcnt(0)
	s_barrier
	s_setprio 1
	s_waitcnt lgkmcnt(0)
	v_mfma_f32_16x16x32_bf16 v[60:63], v[96:99], v[160:163], v[60:63]
	v_mfma_f32_16x16x32_bf16 v[56:59], v[120:123], v[160:163], v[56:59]
	v_mfma_f32_16x16x32_bf16 v[44:47], v[96:99], v[168:171], v[44:47]
	v_mfma_f32_16x16x32_bf16 v[40:43], v[120:123], v[168:171], v[40:43]
	v_mfma_f32_16x16x32_bf16 v[28:31], v[96:99], v[176:179], v[28:31]
	v_mfma_f32_16x16x32_bf16 v[24:27], v[120:123], v[176:179], v[24:27]
	v_mfma_f32_16x16x32_bf16 v[12:15], v[96:99], v[202:205], v[12:15]
	v_mfma_f32_16x16x32_bf16 v[8:11], v[120:123], v[202:205], v[8:11]
	v_mfma_f32_16x16x32_bf16 v[60:63], v[108:111], v[164:167], v[60:63]
	v_mfma_f32_16x16x32_bf16 v[56:59], v[128:131], v[164:167], v[56:59]
	v_mfma_f32_16x16x32_bf16 v[44:47], v[108:111], v[172:175], v[44:47]
	v_mfma_f32_16x16x32_bf16 v[40:43], v[128:131], v[172:175], v[40:43]
	v_mfma_f32_16x16x32_bf16 v[28:31], v[108:111], v[180:183], v[28:31]
	v_mfma_f32_16x16x32_bf16 v[24:27], v[128:131], v[180:183], v[24:27]
	v_mfma_f32_16x16x32_bf16 v[12:15], v[108:111], v[206:209], v[12:15]
	v_mfma_f32_16x16x32_bf16 v[8:11], v[128:131], v[206:209], v[8:11]
	s_setprio 0
	s_setprio 1
	v_mfma_f32_16x16x32_bf16 v[52:55], v[144:147], v[160:163], v[52:55]
	v_mfma_f32_16x16x32_bf16 v[48:51], v[152:155], v[160:163], v[48:51]
	v_mfma_f32_16x16x32_bf16 v[36:39], v[144:147], v[168:171], v[36:39]
	v_mfma_f32_16x16x32_bf16 v[32:35], v[152:155], v[168:171], v[32:35]
	v_mfma_f32_16x16x32_bf16 v[20:23], v[144:147], v[176:179], v[20:23]
	v_mfma_f32_16x16x32_bf16 v[16:19], v[152:155], v[176:179], v[16:19]
	v_mfma_f32_16x16x32_bf16 v[4:7], v[144:147], v[202:205], v[4:7]
	v_mfma_f32_16x16x32_bf16 v[0:3], v[152:155], v[202:205], v[0:3]
	v_mfma_f32_16x16x32_bf16 v[52:55], v[148:151], v[164:167], v[52:55]
	v_mfma_f32_16x16x32_bf16 v[48:51], v[156:159], v[164:167], v[48:51]
	v_mfma_f32_16x16x32_bf16 v[36:39], v[148:151], v[172:175], v[36:39]
	v_mfma_f32_16x16x32_bf16 v[32:35], v[156:159], v[172:175], v[32:35]
	v_mfma_f32_16x16x32_bf16 v[20:23], v[148:151], v[180:183], v[20:23]
	v_mfma_f32_16x16x32_bf16 v[16:19], v[156:159], v[180:183], v[16:19]
	v_mfma_f32_16x16x32_bf16 v[4:7], v[148:151], v[206:209], v[4:7]
	v_mfma_f32_16x16x32_bf16 v[0:3], v[156:159], v[206:209], v[0:3]
	s_setprio 0
	s_barrier
	s_add_i32 s73, 0, 0x18000
	s_add_i32 s74, 0, 0x1c000
	s_add_u32 s48, s48, 0x40000
	s_addc_u32 s49, s49, 0
	s_mov_b32 m0, s56
	v_lshl_add_u64 v[218:219], s[48:49], 0, v[184:185]
	global_load_lds_dwordx4 v[218:219], off
	v_lshl_add_u64 v[218:219], s[48:49], 0, v[188:189]
	s_mov_b32 m0, s57
	s_nop 0
	global_load_lds_dwordx4 v[218:219], off
	v_add_u32_e32 v128, s73, v220
	v_add_u32_e32 v156, s74, v220
	ds_read_b128 v[96:99], v128
	ds_read_b128 v[108:111], v128 offset:1024
	ds_read_b128 v[120:123], v128 offset:2048
	ds_read_b128 v[128:131], v128 offset:3072
	ds_read_b128 v[144:147], v156
	ds_read_b128 v[148:151], v156 offset:1024
	ds_read_b128 v[152:155], v156 offset:2048
	ds_read_b128 v[156:159], v156 offset:3072
	ds_read_b128 v[160:163], v224 offset:32768
	ds_read_b128 v[164:167], v224 offset:33792
	ds_read_b128 v[168:171], v224 offset:34816
	ds_read_b128 v[172:175], v224 offset:35840
	ds_read_b128 v[176:179], v224 offset:36864
	ds_read_b128 v[180:183], v224 offset:37888
	ds_read_b128 v[202:205], v224 offset:38912
	ds_read_b128 v[206:209], v224 offset:39936
	s_waitcnt vmcnt(8)
	s_waitcnt lgkmcnt(0)
	s_barrier
	s_setprio 1
	s_waitcnt lgkmcnt(0)
	v_mfma_f32_16x16x32_bf16 v[140:143], v[96:99], v[160:163], v[140:143]
	v_mfma_f32_16x16x32_bf16 v[136:139], v[120:123], v[160:163], v[136:139]
	v_mfma_f32_16x16x32_bf16 v[116:119], v[96:99], v[168:171], v[116:119]
	v_mfma_f32_16x16x32_bf16 v[112:115], v[120:123], v[168:171], v[112:115]
	v_mfma_f32_16x16x32_bf16 v[92:95], v[96:99], v[176:179], v[92:95]
	v_mfma_f32_16x16x32_bf16 v[88:91], v[120:123], v[176:179], v[88:91]
	v_mfma_f32_16x16x32_bf16 v[76:79], v[96:99], v[202:205], v[76:79]
	v_mfma_f32_16x16x32_bf16 v[72:75], v[120:123], v[202:205], v[72:75]
	v_mfma_f32_16x16x32_bf16 v[140:143], v[108:111], v[164:167], v[140:143]
	v_mfma_f32_16x16x32_bf16 v[136:139], v[128:131], v[164:167], v[136:139]
	v_mfma_f32_16x16x32_bf16 v[116:119], v[108:111], v[172:175], v[116:119]
	v_mfma_f32_16x16x32_bf16 v[112:115], v[128:131], v[172:175], v[112:115]
	v_mfma_f32_16x16x32_bf16 v[92:95], v[108:111], v[180:183], v[92:95]
	v_mfma_f32_16x16x32_bf16 v[88:91], v[128:131], v[180:183], v[88:91]
	v_mfma_f32_16x16x32_bf16 v[76:79], v[108:111], v[206:209], v[76:79]
	v_mfma_f32_16x16x32_bf16 v[72:75], v[128:131], v[206:209], v[72:75]
	s_setprio 0
	s_setprio 1
	v_mfma_f32_16x16x32_bf16 v[132:135], v[144:147], v[160:163], v[132:135]
	v_mfma_f32_16x16x32_bf16 v[124:127], v[152:155], v[160:163], v[124:127]
	v_mfma_f32_16x16x32_bf16 v[104:107], v[144:147], v[168:171], v[104:107]
	v_mfma_f32_16x16x32_bf16 v[100:103], v[152:155], v[168:171], v[100:103]
	v_mfma_f32_16x16x32_bf16 v[84:87], v[144:147], v[176:179], v[84:87]
	v_mfma_f32_16x16x32_bf16 v[80:83], v[152:155], v[176:179], v[80:83]
	v_mfma_f32_16x16x32_bf16 v[68:71], v[144:147], v[202:205], v[68:71]
	v_mfma_f32_16x16x32_bf16 v[64:67], v[152:155], v[202:205], v[64:67]
	v_mfma_f32_16x16x32_bf16 v[132:135], v[148:151], v[164:167], v[132:135]
	v_mfma_f32_16x16x32_bf16 v[124:127], v[156:159], v[164:167], v[124:127]
	v_mfma_f32_16x16x32_bf16 v[104:107], v[148:151], v[172:175], v[104:107]
	v_mfma_f32_16x16x32_bf16 v[100:103], v[156:159], v[172:175], v[100:103]
	v_mfma_f32_16x16x32_bf16 v[84:87], v[148:151], v[180:183], v[84:87]
	v_mfma_f32_16x16x32_bf16 v[80:83], v[156:159], v[180:183], v[80:83]
	v_mfma_f32_16x16x32_bf16 v[68:71], v[148:151], v[206:209], v[68:71]
	v_mfma_f32_16x16x32_bf16 v[64:67], v[156:159], v[206:209], v[64:67]
	s_setprio 0
	s_barrier
	s_add_i32 s48, s73, s53
	v_lshl_add_u64 v[210:211], v[210:211], 0, s[20:21]
	s_mov_b32 m0, s48
	s_nop 0
	global_load_lds_dwordx4 v[210:211], off
	s_add_i32 m0, s48, 0x2000
	s_add_u32 s46, s46, 0x40080
	v_lshl_add_u64 v[210:211], v[212:213], 0, s[20:21]
	s_addc_u32 s47, s47, 0
	s_add_i32 s48, s74, s53
	global_load_lds_dwordx4 v[210:211], off
	v_lshl_add_u64 v[210:211], s[46:47], 0, v[186:187]
	s_mov_b32 m0, s48
	s_nop 0
	global_load_lds_dwordx4 v[210:211], off
	v_lshl_add_u64 v[210:211], s[46:47], 0, v[190:191]
	s_add_i32 m0, s48, 0x2000
	s_nop 0
	global_load_lds_dwordx4 v[210:211], off
	v_lshl_add_u64 v[210:211], v[214:215], 0, s[20:21]
	s_mov_b32 m0, s59
	s_nop 0
	global_load_lds_dwordx4 v[210:211], off
	v_lshl_add_u64 v[210:211], v[216:217], 0, s[20:21]
	s_mov_b32 m0, s60
	s_nop 0
	global_load_lds_dwordx4 v[210:211], off
	ds_read_b128 v[160:163], v224 offset:49152
	ds_read_b128 v[164:167], v224 offset:50176
	ds_read_b128 v[168:171], v224 offset:51200
	ds_read_b128 v[172:175], v224 offset:52224
	ds_read_b128 v[176:179], v224 offset:53248
	ds_read_b128 v[180:183], v224 offset:54272
	ds_read_b128 v[202:205], v224 offset:55296
	ds_read_b128 v[206:209], v224 offset:56320
	s_waitcnt vmcnt(8)
	s_waitcnt lgkmcnt(0)
	s_barrier
	s_setprio 1
	s_waitcnt lgkmcnt(0)
	v_mfma_f32_16x16x32_bf16 v[60:63], v[96:99], v[160:163], v[60:63]
	v_mfma_f32_16x16x32_bf16 v[56:59], v[120:123], v[160:163], v[56:59]
	v_mfma_f32_16x16x32_bf16 v[44:47], v[96:99], v[168:171], v[44:47]
	v_mfma_f32_16x16x32_bf16 v[40:43], v[120:123], v[168:171], v[40:43]
	v_mfma_f32_16x16x32_bf16 v[28:31], v[96:99], v[176:179], v[28:31]
	v_mfma_f32_16x16x32_bf16 v[24:27], v[120:123], v[176:179], v[24:27]
	v_mfma_f32_16x16x32_bf16 v[12:15], v[96:99], v[202:205], v[12:15]
	v_mfma_f32_16x16x32_bf16 v[8:11], v[120:123], v[202:205], v[8:11]
	v_mfma_f32_16x16x32_bf16 v[60:63], v[108:111], v[164:167], v[60:63]
	v_mfma_f32_16x16x32_bf16 v[56:59], v[128:131], v[164:167], v[56:59]
	v_mfma_f32_16x16x32_bf16 v[44:47], v[108:111], v[172:175], v[44:47]
	v_mfma_f32_16x16x32_bf16 v[40:43], v[128:131], v[172:175], v[40:43]
	v_mfma_f32_16x16x32_bf16 v[28:31], v[108:111], v[180:183], v[28:31]
	v_mfma_f32_16x16x32_bf16 v[24:27], v[128:131], v[180:183], v[24:27]
	v_mfma_f32_16x16x32_bf16 v[12:15], v[108:111], v[206:209], v[12:15]
	v_mfma_f32_16x16x32_bf16 v[8:11], v[128:131], v[206:209], v[8:11]
	s_setprio 0
	s_setprio 1
	v_mfma_f32_16x16x32_bf16 v[52:55], v[144:147], v[160:163], v[52:55]
	v_mfma_f32_16x16x32_bf16 v[48:51], v[152:155], v[160:163], v[48:51]
	v_mfma_f32_16x16x32_bf16 v[36:39], v[144:147], v[168:171], v[36:39]
	v_mfma_f32_16x16x32_bf16 v[32:35], v[152:155], v[168:171], v[32:35]
	v_mfma_f32_16x16x32_bf16 v[20:23], v[144:147], v[176:179], v[20:23]
	v_mfma_f32_16x16x32_bf16 v[16:19], v[152:155], v[176:179], v[16:19]
	v_mfma_f32_16x16x32_bf16 v[4:7], v[144:147], v[202:205], v[4:7]
	v_mfma_f32_16x16x32_bf16 v[0:3], v[152:155], v[202:205], v[0:3]
	v_mfma_f32_16x16x32_bf16 v[52:55], v[148:151], v[164:167], v[52:55]
	v_mfma_f32_16x16x32_bf16 v[48:51], v[156:159], v[164:167], v[48:51]
	v_mfma_f32_16x16x32_bf16 v[36:39], v[148:151], v[172:175], v[36:39]
	v_mfma_f32_16x16x32_bf16 v[32:35], v[156:159], v[172:175], v[32:35]
	v_mfma_f32_16x16x32_bf16 v[20:23], v[148:151], v[180:183], v[20:23]
	v_mfma_f32_16x16x32_bf16 v[16:19], v[156:159], v[180:183], v[16:19]
	v_mfma_f32_16x16x32_bf16 v[4:7], v[148:151], v[206:209], v[4:7]
	v_mfma_f32_16x16x32_bf16 v[0:3], v[156:159], v[206:209], v[0:3]
	s_setprio 0
	s_barrier
	s_add_i32 s72, s72, 2
	s_add_u32 s44, s44, 0x100
	s_addc_u32 s45, s45, 0
	s_add_u32 s43, s43, 0x100
	s_addc_u32 s67, s67, 0
	s_cmp_gt_u32 s72, 13
	s_cbranch_scc0 .LBB0_492
	s_and_b64 vcc, exec, s[26:27]
	s_cbranch_vccz .LBB0_495
	s_barrier

.LBB0_577:
	s_add_u32 s62, s8, 0xfffc0080
	s_addc_u32 s63, s9, -1
	s_cmp_eq_u32 s86, 12
	s_cselect_b32 s65, s10, s63
	s_cselect_b32 s64, s11, s62
	s_cselect_b32 s63, s51, s61
	s_cselect_b32 s62, s53, s59
	v_lshl_add_u64 v[220:221], s[8:9], 0, v[212:213]
	s_add_i32 m0, s74, 0xc000
	s_nop 0
	global_load_lds_dwordx4 v[220:221], off
	v_lshl_add_u64 v[220:221], s[8:9], 0, v[214:215]
	s_add_i32 m0, s74, 0xe000
	s_nop 0
	global_load_lds_dwordx4 v[220:221], off
	ds_read_b128 v[108:111], v245
	ds_read_b128 v[116:119], v245 offset:1024
	ds_read_b128 v[120:123], v245 offset:2048
	ds_read_b128 v[124:127], v245 offset:3072
	ds_read_b128 v[128:131], v246
	ds_read_b128 v[132:135], v246 offset:1024
	ds_read_b128 v[136:139], v246 offset:2048
	ds_read_b128 v[140:143], v246 offset:3072
	ds_read_b128 v[144:147], v247
	ds_read_b128 v[148:151], v247 offset:1024
	ds_read_b128 v[168:171], v247 offset:2048
	ds_read_b128 v[172:175], v247 offset:3072
	ds_read_b128 v[176:179], v247 offset:4096
	ds_read_b128 v[180:183], v247 offset:5120
	ds_read_b128 v[184:187], v247 offset:6144
	ds_read_b128 v[188:191], v247 offset:7168
	s_waitcnt vmcnt(8)
	s_waitcnt lgkmcnt(0)
	s_barrier
	s_setprio 1
	s_waitcnt lgkmcnt(0)
	v_mfma_f32_16x16x32_bf16 v[52:55], v[108:111], v[144:147], v[52:55]
	v_mfma_f32_16x16x32_bf16 v[44:47], v[120:123], v[144:147], v[44:47]
	v_mfma_f32_16x16x32_bf16 v[164:167], v[108:111], v[168:171], v[164:167]
	v_mfma_f32_16x16x32_bf16 v[68:71], v[120:123], v[168:171], v[68:71]
	v_mfma_f32_16x16x32_bf16 v[160:163], v[108:111], v[176:179], v[160:163]
	v_mfma_f32_16x16x32_bf16 v[60:63], v[120:123], v[176:179], v[60:63]
	v_mfma_f32_16x16x32_bf16 v[84:87], v[108:111], v[184:187], v[84:87]
	v_mfma_f32_16x16x32_bf16 v[80:83], v[120:123], v[184:187], v[80:83]
	v_mfma_f32_16x16x32_bf16 v[52:55], v[116:119], v[148:151], v[52:55]
	v_mfma_f32_16x16x32_bf16 v[44:47], v[124:127], v[148:151], v[44:47]
	v_mfma_f32_16x16x32_bf16 v[164:167], v[116:119], v[172:175], v[164:167]
	v_mfma_f32_16x16x32_bf16 v[68:71], v[124:127], v[172:175], v[68:71]
	v_mfma_f32_16x16x32_bf16 v[160:163], v[116:119], v[180:183], v[160:163]
	v_mfma_f32_16x16x32_bf16 v[60:63], v[124:127], v[180:183], v[60:63]
	v_mfma_f32_16x16x32_bf16 v[84:87], v[116:119], v[188:191], v[84:87]
	v_mfma_f32_16x16x32_bf16 v[80:83], v[124:127], v[188:191], v[80:83]
	s_setprio 0
	s_setprio 1
	v_mfma_f32_16x16x32_bf16 v[36:39], v[128:131], v[144:147], v[36:39]
	v_mfma_f32_16x16x32_bf16 v[28:31], v[136:139], v[144:147], v[28:31]
	v_mfma_f32_16x16x32_bf16 v[64:67], v[136:139], v[168:171], v[64:67]
	v_mfma_f32_16x16x32_bf16 v[56:59], v[136:139], v[176:179], v[56:59]
	v_mfma_f32_16x16x32_bf16 v[76:79], v[128:131], v[184:187], v[76:79]
	v_mfma_f32_16x16x32_bf16 v[72:75], v[136:139], v[184:187], v[72:75]
	v_mfma_f32_16x16x32_bf16 v[36:39], v[132:135], v[148:151], v[36:39]
	v_mfma_f32_16x16x32_bf16 v[28:31], v[140:143], v[148:151], v[28:31]
	v_mfma_f32_16x16x32_bf16 v[144:147], v[128:131], v[168:171], v[152:155]
	v_mfma_f32_16x16x32_bf16 v[64:67], v[140:143], v[172:175], v[64:67]
	v_mfma_f32_16x16x32_bf16 v[148:151], v[128:131], v[176:179], v[156:159]
	v_mfma_f32_16x16x32_bf16 v[56:59], v[140:143], v[180:183], v[56:59]
	v_mfma_f32_16x16x32_bf16 v[76:79], v[132:135], v[188:191], v[76:79]
	v_mfma_f32_16x16x32_bf16 v[72:75], v[140:143], v[188:191], v[72:75]
	v_mfma_f32_16x16x32_bf16 v[144:147], v[132:135], v[172:175], v[144:147]
	v_mfma_f32_16x16x32_bf16 v[148:151], v[132:135], v[180:183], v[148:151]
	s_setprio 0
	s_barrier
	s_add_i32 s87, s89, s73
	v_lshl_add_u64 v[220:221], s[62:63], 0, v[194:195]
	s_mov_b32 m0, s87
	s_nop 0
	global_load_lds_dwordx4 v[220:221], off
	s_add_i32 m0, s87, 0x2000
	s_add_u32 s96, s62, 0x40000
	v_lshl_add_u64 v[222:223], s[62:63], 0, v[200:201]
	s_addc_u32 s97, s63, 0
	s_add_i32 s87, s90, s73
	global_load_lds_dwordx4 v[222:223], off
	v_lshl_add_u64 v[224:225], s[96:97], 0, v[194:195]
	s_mov_b32 m0, s87
	v_lshl_add_u64 v[226:227], s[64:65], 0, v[198:199]
	global_load_lds_dwordx4 v[224:225], off
	v_lshl_add_u64 v[224:225], s[96:97], 0, v[200:201]
	s_add_i32 m0, s87, 0x2000
	s_nop 0
	global_load_lds_dwordx4 v[224:225], off
	v_lshl_add_u64 v[224:225], s[64:65], 0, v[192:193]
	s_mov_b32 m0, s74
	s_nop 0
	global_load_lds_dwordx4 v[224:225], off
	s_mov_b32 m0, s75
	s_nop 0
	global_load_lds_dwordx4 v[226:227], off
	ds_read_b128 v[152:155], v247 offset:16384
	ds_read_b128 v[156:159], v247 offset:17408
	ds_read_b128 v[168:171], v247 offset:18432
	ds_read_b128 v[172:175], v247 offset:19456
	ds_read_b128 v[176:179], v247 offset:20480
	ds_read_b128 v[180:183], v247 offset:21504
	ds_read_b128 v[184:187], v247 offset:22528
	ds_read_b128 v[188:191], v247 offset:23552
	s_waitcnt vmcnt(8)
	s_waitcnt lgkmcnt(0)
	s_barrier
	s_setprio 1
	s_waitcnt lgkmcnt(0)
	v_mfma_f32_16x16x32_bf16 v[112:115], v[108:111], v[152:155], v[112:115]
	v_mfma_f32_16x16x32_bf16 v[20:23], v[120:123], v[152:155], v[20:23]
	v_mfma_f32_16x16x32_bf16 v[104:107], v[108:111], v[168:171], v[104:107]
	v_mfma_f32_16x16x32_bf16 v[16:19], v[120:123], v[168:171], v[16:19]
	v_mfma_f32_16x16x32_bf16 v[92:95], v[108:111], v[176:179], v[92:95]
	v_mfma_f32_16x16x32_bf16 v[4:7], v[120:123], v[176:179], v[4:7]
	v_mfma_f32_16x16x32_bf16 v[48:51], v[108:111], v[184:187], v[48:51]
	v_mfma_f32_16x16x32_bf16 v[40:43], v[120:123], v[184:187], v[40:43]
	v_mfma_f32_16x16x32_bf16 v[112:115], v[116:119], v[156:159], v[112:115]
	v_mfma_f32_16x16x32_bf16 v[20:23], v[124:127], v[156:159], v[20:23]
	v_mfma_f32_16x16x32_bf16 v[104:107], v[116:119], v[172:175], v[104:107]
	v_mfma_f32_16x16x32_bf16 v[16:19], v[124:127], v[172:175], v[16:19]
	v_mfma_f32_16x16x32_bf16 v[92:95], v[116:119], v[180:183], v[92:95]
	v_mfma_f32_16x16x32_bf16 v[4:7], v[124:127], v[180:183], v[4:7]
	v_mfma_f32_16x16x32_bf16 v[48:51], v[116:119], v[188:191], v[48:51]
	v_mfma_f32_16x16x32_bf16 v[40:43], v[124:127], v[188:191], v[40:43]
	s_setprio 0
	s_setprio 1
	v_mfma_f32_16x16x32_bf16 v[100:103], v[128:131], v[152:155], v[100:103]
	v_mfma_f32_16x16x32_bf16 v[12:15], v[136:139], v[152:155], v[12:15]
	v_mfma_f32_16x16x32_bf16 v[96:99], v[128:131], v[168:171], v[96:99]
	v_mfma_f32_16x16x32_bf16 v[8:11], v[136:139], v[168:171], v[8:11]
	v_mfma_f32_16x16x32_bf16 v[88:91], v[128:131], v[176:179], v[88:91]
	v_mfma_f32_16x16x32_bf16 v[0:3], v[136:139], v[176:179], v[0:3]
	v_mfma_f32_16x16x32_bf16 v[32:35], v[128:131], v[184:187], v[32:35]
	v_mfma_f32_16x16x32_bf16 v[24:27], v[136:139], v[184:187], v[24:27]
	v_mfma_f32_16x16x32_bf16 v[100:103], v[132:135], v[156:159], v[100:103]
	v_mfma_f32_16x16x32_bf16 v[12:15], v[140:143], v[156:159], v[12:15]
	v_mfma_f32_16x16x32_bf16 v[96:99], v[132:135], v[172:175], v[96:99]
	v_mfma_f32_16x16x32_bf16 v[8:11], v[140:143], v[172:175], v[8:11]
	v_mfma_f32_16x16x32_bf16 v[88:91], v[132:135], v[180:183], v[88:91]
	v_mfma_f32_16x16x32_bf16 v[0:3], v[140:143], v[180:183], v[0:3]
	v_mfma_f32_16x16x32_bf16 v[32:35], v[132:135], v[188:191], v[32:35]
	v_mfma_f32_16x16x32_bf16 v[24:27], v[140:143], v[188:191], v[24:27]
	s_setprio 0
	s_barrier
	s_add_i32 s87, 0, 0x18000
	s_add_i32 s96, 0, 0x1c000
	s_add_u32 s64, s64, 0x40000
	s_addc_u32 s65, s65, 0
	s_mov_b32 m0, s76
	v_lshl_add_u64 v[228:229], s[64:65], 0, v[192:193]
	global_load_lds_dwordx4 v[228:229], off
	v_lshl_add_u64 v[228:229], s[64:65], 0, v[198:199]
	s_mov_b32 m0, s77
	s_nop 0
	global_load_lds_dwordx4 v[228:229], off
	v_add_u32_e32 v124, s87, v205
	v_add_u32_e32 v140, s96, v205
	ds_read_b128 v[108:111], v124
	ds_read_b128 v[116:119], v124 offset:1024
	ds_read_b128 v[120:123], v124 offset:2048
	ds_read_b128 v[124:127], v124 offset:3072
	ds_read_b128 v[128:131], v140
	ds_read_b128 v[132:135], v140 offset:1024
	ds_read_b128 v[136:139], v140 offset:2048
	ds_read_b128 v[140:143], v140 offset:3072
	ds_read_b128 v[152:155], v247 offset:32768
	ds_read_b128 v[156:159], v247 offset:33792
	ds_read_b128 v[168:171], v247 offset:34816
	ds_read_b128 v[172:175], v247 offset:35840
	ds_read_b128 v[176:179], v247 offset:36864
	ds_read_b128 v[180:183], v247 offset:37888
	ds_read_b128 v[184:187], v247 offset:38912
	ds_read_b128 v[188:191], v247 offset:39936
	s_waitcnt vmcnt(8)
	s_waitcnt lgkmcnt(0)
	s_barrier
	s_setprio 1
	s_waitcnt lgkmcnt(0)
	v_mfma_f32_16x16x32_bf16 v[52:55], v[108:111], v[152:155], v[52:55]
	v_mfma_f32_16x16x32_bf16 v[44:47], v[120:123], v[152:155], v[44:47]
	v_mfma_f32_16x16x32_bf16 v[164:167], v[108:111], v[168:171], v[164:167]
	v_mfma_f32_16x16x32_bf16 v[68:71], v[120:123], v[168:171], v[68:71]
	v_mfma_f32_16x16x32_bf16 v[160:163], v[108:111], v[176:179], v[160:163]
	v_mfma_f32_16x16x32_bf16 v[60:63], v[120:123], v[176:179], v[60:63]
	v_mfma_f32_16x16x32_bf16 v[84:87], v[108:111], v[184:187], v[84:87]
	v_mfma_f32_16x16x32_bf16 v[80:83], v[120:123], v[184:187], v[80:83]
	v_mfma_f32_16x16x32_bf16 v[52:55], v[116:119], v[156:159], v[52:55]
	v_mfma_f32_16x16x32_bf16 v[44:47], v[124:127], v[156:159], v[44:47]
	v_mfma_f32_16x16x32_bf16 v[164:167], v[116:119], v[172:175], v[164:167]
	v_mfma_f32_16x16x32_bf16 v[68:71], v[124:127], v[172:175], v[68:71]
	v_mfma_f32_16x16x32_bf16 v[160:163], v[116:119], v[180:183], v[160:163]
	v_mfma_f32_16x16x32_bf16 v[60:63], v[124:127], v[180:183], v[60:63]
	v_mfma_f32_16x16x32_bf16 v[84:87], v[116:119], v[188:191], v[84:87]
	v_mfma_f32_16x16x32_bf16 v[80:83], v[124:127], v[188:191], v[80:83]
	s_setprio 0
	s_setprio 1
	v_mfma_f32_16x16x32_bf16 v[144:147], v[128:131], v[168:171], v[144:147]
	v_mfma_f32_16x16x32_bf16 v[36:39], v[128:131], v[152:155], v[36:39]
	v_mfma_f32_16x16x32_bf16 v[28:31], v[136:139], v[152:155], v[28:31]
	v_mfma_f32_16x16x32_bf16 v[152:155], v[132:135], v[172:175], v[144:147]
	v_mfma_f32_16x16x32_bf16 v[64:67], v[136:139], v[168:171], v[64:67]
	v_mfma_f32_16x16x32_bf16 v[144:147], v[128:131], v[176:179], v[148:151]
	v_mfma_f32_16x16x32_bf16 v[56:59], v[136:139], v[176:179], v[56:59]
	v_mfma_f32_16x16x32_bf16 v[76:79], v[128:131], v[184:187], v[76:79]
	v_mfma_f32_16x16x32_bf16 v[72:75], v[136:139], v[184:187], v[72:75]
	v_mfma_f32_16x16x32_bf16 v[36:39], v[132:135], v[156:159], v[36:39]
	v_mfma_f32_16x16x32_bf16 v[28:31], v[140:143], v[156:159], v[28:31]
	v_mfma_f32_16x16x32_bf16 v[64:67], v[140:143], v[172:175], v[64:67]
	v_mfma_f32_16x16x32_bf16 v[156:159], v[132:135], v[180:183], v[144:147]
	v_mfma_f32_16x16x32_bf16 v[56:59], v[140:143], v[180:183], v[56:59]
	v_mfma_f32_16x16x32_bf16 v[76:79], v[132:135], v[188:191], v[76:79]
	v_mfma_f32_16x16x32_bf16 v[72:75], v[140:143], v[188:191], v[72:75]
	s_setprio 0
	s_barrier
	s_add_i32 s64, s87, s73
	v_lshl_add_u64 v[220:221], v[220:221], 0, s[20:21]
	s_mov_b32 m0, s64
	s_nop 0
	global_load_lds_dwordx4 v[220:221], off
	s_add_i32 m0, s64, 0x2000
	s_add_u32 s62, s62, 0x40080
	v_lshl_add_u64 v[220:221], v[222:223], 0, s[20:21]
	s_addc_u32 s63, s63, 0
	s_add_i32 s64, s96, s73
	global_load_lds_dwordx4 v[220:221], off
	v_lshl_add_u64 v[220:221], s[62:63], 0, v[194:195]
	s_mov_b32 m0, s64
	s_nop 0
	global_load_lds_dwordx4 v[220:221], off
	v_lshl_add_u64 v[220:221], s[62:63], 0, v[200:201]
	s_add_i32 m0, s64, 0x2000
	s_nop 0
	global_load_lds_dwordx4 v[220:221], off
	v_lshl_add_u64 v[220:221], v[224:225], 0, s[20:21]
	s_mov_b32 m0, s80
	s_nop 0
	global_load_lds_dwordx4 v[220:221], off
	v_lshl_add_u64 v[220:221], v[226:227], 0, s[20:21]
	s_mov_b32 m0, s81
	s_nop 0
	global_load_lds_dwordx4 v[220:221], off
	ds_read_b128 v[144:147], v247 offset:49152
	ds_read_b128 v[148:151], v247 offset:50176
	ds_read_b128 v[168:171], v247 offset:51200
	ds_read_b128 v[172:175], v247 offset:52224
	ds_read_b128 v[176:179], v247 offset:53248
	ds_read_b128 v[180:183], v247 offset:54272
	ds_read_b128 v[184:187], v247 offset:55296
	ds_read_b128 v[188:191], v247 offset:56320
	s_waitcnt vmcnt(8)
	s_waitcnt lgkmcnt(0)
	s_barrier
	s_setprio 1
	s_waitcnt lgkmcnt(0)
	v_mfma_f32_16x16x32_bf16 v[112:115], v[108:111], v[144:147], v[112:115]
	v_mfma_f32_16x16x32_bf16 v[20:23], v[120:123], v[144:147], v[20:23]
	v_mfma_f32_16x16x32_bf16 v[104:107], v[108:111], v[168:171], v[104:107]
	v_mfma_f32_16x16x32_bf16 v[16:19], v[120:123], v[168:171], v[16:19]
	v_mfma_f32_16x16x32_bf16 v[92:95], v[108:111], v[176:179], v[92:95]
	v_mfma_f32_16x16x32_bf16 v[4:7], v[120:123], v[176:179], v[4:7]
	v_mfma_f32_16x16x32_bf16 v[48:51], v[108:111], v[184:187], v[48:51]
	v_mfma_f32_16x16x32_bf16 v[40:43], v[120:123], v[184:187], v[40:43]
	v_mfma_f32_16x16x32_bf16 v[112:115], v[116:119], v[148:151], v[112:115]
	v_mfma_f32_16x16x32_bf16 v[20:23], v[124:127], v[148:151], v[20:23]
	v_mfma_f32_16x16x32_bf16 v[104:107], v[116:119], v[172:175], v[104:107]
	v_mfma_f32_16x16x32_bf16 v[16:19], v[124:127], v[172:175], v[16:19]
	v_mfma_f32_16x16x32_bf16 v[92:95], v[116:119], v[180:183], v[92:95]
	v_mfma_f32_16x16x32_bf16 v[4:7], v[124:127], v[180:183], v[4:7]
	v_mfma_f32_16x16x32_bf16 v[48:51], v[116:119], v[188:191], v[48:51]
	v_mfma_f32_16x16x32_bf16 v[40:43], v[124:127], v[188:191], v[40:43]
	s_setprio 0
	s_setprio 1
	v_mfma_f32_16x16x32_bf16 v[100:103], v[128:131], v[144:147], v[100:103]
	v_mfma_f32_16x16x32_bf16 v[12:15], v[136:139], v[144:147], v[12:15]
	v_mfma_f32_16x16x32_bf16 v[96:99], v[128:131], v[168:171], v[96:99]
	v_mfma_f32_16x16x32_bf16 v[8:11], v[136:139], v[168:171], v[8:11]
	v_mfma_f32_16x16x32_bf16 v[88:91], v[128:131], v[176:179], v[88:91]
	v_mfma_f32_16x16x32_bf16 v[0:3], v[136:139], v[176:179], v[0:3]
	v_mfma_f32_16x16x32_bf16 v[32:35], v[128:131], v[184:187], v[32:35]
	v_mfma_f32_16x16x32_bf16 v[24:27], v[136:139], v[184:187], v[24:27]
	v_mfma_f32_16x16x32_bf16 v[100:103], v[132:135], v[148:151], v[100:103]
	v_mfma_f32_16x16x32_bf16 v[12:15], v[140:143], v[148:151], v[12:15]
	v_mfma_f32_16x16x32_bf16 v[96:99], v[132:135], v[172:175], v[96:99]
	v_mfma_f32_16x16x32_bf16 v[8:11], v[140:143], v[172:175], v[8:11]
	v_mfma_f32_16x16x32_bf16 v[88:91], v[132:135], v[180:183], v[88:91]
	v_mfma_f32_16x16x32_bf16 v[0:3], v[140:143], v[180:183], v[0:3]
	v_mfma_f32_16x16x32_bf16 v[32:35], v[132:135], v[188:191], v[32:35]
	v_mfma_f32_16x16x32_bf16 v[24:27], v[140:143], v[188:191], v[24:27]
	s_setprio 0
	s_barrier
	s_add_i32 s86, s86, 2
	s_add_u32 s8, s8, 0x100
	s_addc_u32 s9, s9, 0
	s_add_u32 s59, s59, 0x100
	s_addc_u32 s61, s61, 0
	s_cmp_gt_u32 s86, 13
	s_cbranch_scc0 .LBB0_577
	s_and_b64 vcc, exec, s[26:27]
	s_cbranch_vccz .LBB0_580
	s_barrier

.LBB0_687:
	s_add_u32 s20, s18, 0x100
	s_addc_u32 s21, s19, 0
	s_cmp_eq_u32 s47, 40
	s_cselect_b32 s25, s5, s21
	s_cselect_b32 s24, s4, s20
	s_cselect_b32 s23, s15, s46
	s_cselect_b32 s22, s14, s45
	v_lshl_add_u64 v[214:215], s[18:19], 0, v[172:173]
	s_add_i32 m0, s29, 0xc000
	s_nop 0
	global_load_lds_dwordx4 v[214:215], off
	v_lshl_add_u64 v[214:215], s[18:19], 0, v[174:175]
	s_add_i32 m0, s29, 0xe000
	s_nop 0
	global_load_lds_dwordx4 v[214:215], off
	ds_read_b128 v[128:131], v195
	ds_read_b128 v[132:135], v195 offset:1024
	ds_read_b128 v[136:139], v195 offset:2048
	ds_read_b128 v[140:143], v195 offset:3072
	ds_read_b128 v[144:147], v196
	ds_read_b128 v[148:151], v196 offset:1024
	ds_read_b128 v[152:155], v196 offset:2048
	ds_read_b128 v[156:159], v196 offset:3072
	ds_read_b128 v[160:163], v197
	ds_read_b128 v[180:183], v197 offset:1024
	ds_read_b128 v[184:187], v197 offset:2048
	ds_read_b128 v[188:191], v197 offset:3072
	ds_read_b128 v[198:201], v197 offset:4096
	ds_read_b128 v[202:205], v197 offset:5120
	ds_read_b128 v[206:209], v197 offset:6144
	ds_read_b128 v[210:213], v197 offset:7168
	s_waitcnt vmcnt(8)
	s_cmp_lg_u32 s47, 8
	s_cbranch_scc1 .Lp6_nopf
	v_lshl_add_u32 v252, s43, 8, v192
	v_lshl_or_b32 v254, s44, 8, v194
	v_ashrrev_i32_e32 v255, 31, v254
	v_ashrrev_i32_e32 v253, 31, v252
	v_lshl_add_u64 v[254:255], v[254:255], 1, s[8:9]
	v_lshlrev_b64 v[250:251], 11, v[252:253]
	v_lshl_add_u64 v[250:251], v[254:255], 0, v[250:251]
	global_load_dwordx4 v[224:227], v[250:251], off
	global_load_dwordx4 v[228:231], v[250:251], off offset:256
	v_or_b32_e32 v250, 16, v252
	v_mov_b32_e32 v251, v253
	v_lshlrev_b64 v[250:251], 11, v[250:251]
	v_lshl_add_u64 v[250:251], v[254:255], 0, v[250:251]
	global_load_dwordx4 v[232:235], v[250:251], off
	global_load_dwordx4 v[236:239], v[250:251], off offset:256
	v_or_b32_e32 v250, 32, v252
	v_mov_b32_e32 v251, v253
	v_lshlrev_b64 v[250:251], 11, v[250:251]
	v_lshl_add_u64 v[250:251], v[254:255], 0, v[250:251]
	global_load_dwordx4 v[240:243], v[250:251], off
	global_load_dwordx4 v[244:247], v[250:251], off offset:256
	v_or_b32_e32 v250, 48, v252
	v_mov_b32_e32 v251, v253
	v_lshlrev_b64 v[250:251], 11, v[250:251]
	v_lshl_add_u64 v[250:251], v[254:255], 0, v[250:251]
	global_load_dwordx4 v[252:255], v[250:251], off offset:256
	global_load_dwordx4 v[248:251], v[250:251], off
.Lp6_nopf:
	s_waitcnt lgkmcnt(0)
	s_barrier
	s_setprio 1
	s_waitcnt lgkmcnt(0)
	v_mfma_f32_16x16x32_bf16 v[124:127], v[128:131], v[160:163], v[124:127]
	v_mfma_f32_16x16x32_bf16 v[120:123], v[136:139], v[160:163], v[120:123]
	v_mfma_f32_16x16x32_bf16 v[112:115], v[128:131], v[184:187], v[112:115]
	v_mfma_f32_16x16x32_bf16 v[104:107], v[136:139], v[184:187], v[104:107]
	v_mfma_f32_16x16x32_bf16 v[96:99], v[128:131], v[198:201], v[96:99]
	v_mfma_f32_16x16x32_bf16 v[88:91], v[136:139], v[198:201], v[88:91]
	v_mfma_f32_16x16x32_bf16 v[80:83], v[128:131], v[206:209], v[80:83]
	v_mfma_f32_16x16x32_bf16 v[72:75], v[136:139], v[206:209], v[72:75]
	v_mfma_f32_16x16x32_bf16 v[124:127], v[132:135], v[180:183], v[124:127]
	v_mfma_f32_16x16x32_bf16 v[120:123], v[140:143], v[180:183], v[120:123]
	v_mfma_f32_16x16x32_bf16 v[112:115], v[132:135], v[188:191], v[112:115]
	v_mfma_f32_16x16x32_bf16 v[104:107], v[140:143], v[188:191], v[104:107]
	v_mfma_f32_16x16x32_bf16 v[96:99], v[132:135], v[202:205], v[96:99]
	v_mfma_f32_16x16x32_bf16 v[88:91], v[140:143], v[202:205], v[88:91]
	v_mfma_f32_16x16x32_bf16 v[80:83], v[132:135], v[210:213], v[80:83]
	v_mfma_f32_16x16x32_bf16 v[72:75], v[140:143], v[210:213], v[72:75]
	s_setprio 0
	s_setprio 1
	v_mfma_f32_16x16x32_bf16 v[116:119], v[144:147], v[160:163], v[116:119]
	v_mfma_f32_16x16x32_bf16 v[108:111], v[152:155], v[160:163], v[108:111]
	v_mfma_f32_16x16x32_bf16 v[100:103], v[144:147], v[184:187], v[100:103]
	v_mfma_f32_16x16x32_bf16 v[92:95], v[152:155], v[184:187], v[92:95]
	v_mfma_f32_16x16x32_bf16 v[84:87], v[144:147], v[198:201], v[84:87]
	v_mfma_f32_16x16x32_bf16 v[76:79], v[152:155], v[198:201], v[76:79]
	v_mfma_f32_16x16x32_bf16 v[68:71], v[144:147], v[206:209], v[68:71]
	v_mfma_f32_16x16x32_bf16 v[64:67], v[152:155], v[206:209], v[64:67]
	v_mfma_f32_16x16x32_bf16 v[116:119], v[148:151], v[180:183], v[116:119]
	v_mfma_f32_16x16x32_bf16 v[108:111], v[156:159], v[180:183], v[108:111]
	v_mfma_f32_16x16x32_bf16 v[100:103], v[148:151], v[188:191], v[100:103]
	v_mfma_f32_16x16x32_bf16 v[92:95], v[156:159], v[188:191], v[92:95]
	v_mfma_f32_16x16x32_bf16 v[84:87], v[148:151], v[202:205], v[84:87]
	v_mfma_f32_16x16x32_bf16 v[76:79], v[156:159], v[202:205], v[76:79]
	v_mfma_f32_16x16x32_bf16 v[68:71], v[148:151], v[210:213], v[68:71]
	v_mfma_f32_16x16x32_bf16 v[64:67], v[156:159], v[210:213], v[64:67]
	s_setprio 0
	s_barrier
	s_add_i32 s18, s39, s28
	v_lshl_add_u64 v[214:215], s[22:23], 0, v[166:167]
	s_mov_b32 m0, s18
	s_nop 0
	global_load_lds_dwordx4 v[214:215], off
	s_add_i32 m0, s18, 0x2000
	s_add_u32 s18, s22, 0xb0000
	v_lshl_add_u64 v[216:217], s[22:23], 0, v[170:171]
	s_addc_u32 s19, s23, 0
	s_add_i32 s48, s40, s28
	global_load_lds_dwordx4 v[216:217], off
	v_lshl_add_u64 v[218:219], s[18:19], 0, v[166:167]
	s_mov_b32 m0, s48
	v_lshl_add_u64 v[220:221], s[24:25], 0, v[168:169]
	global_load_lds_dwordx4 v[218:219], off
	v_lshl_add_u64 v[218:219], s[18:19], 0, v[170:171]
	s_add_i32 m0, s48, 0x2000
	s_nop 0
	global_load_lds_dwordx4 v[218:219], off
	v_lshl_add_u64 v[218:219], s[24:25], 0, v[164:165]
	s_mov_b32 m0, s29
	s_nop 0
	global_load_lds_dwordx4 v[218:219], off
	s_mov_b32 m0, s33
	s_nop 0
	global_load_lds_dwordx4 v[220:221], off
	ds_read_b128 v[160:163], v197 offset:16384
	ds_read_b128 v[180:183], v197 offset:17408
	ds_read_b128 v[184:187], v197 offset:18432
	ds_read_b128 v[188:191], v197 offset:19456
	ds_read_b128 v[198:201], v197 offset:20480
	ds_read_b128 v[202:205], v197 offset:21504
	ds_read_b128 v[206:209], v197 offset:22528
	ds_read_b128 v[210:213], v197 offset:23552
	s_waitcnt vmcnt(8)
	s_waitcnt lgkmcnt(0)
	s_barrier
	s_setprio 1
	s_waitcnt lgkmcnt(0)
	v_mfma_f32_16x16x32_bf16 v[60:63], v[128:131], v[160:163], v[60:63]
	v_mfma_f32_16x16x32_bf16 v[56:59], v[136:139], v[160:163], v[56:59]
	v_mfma_f32_16x16x32_bf16 v[48:51], v[128:131], v[184:187], v[48:51]
	v_mfma_f32_16x16x32_bf16 v[40:43], v[136:139], v[184:187], v[40:43]
	v_mfma_f32_16x16x32_bf16 v[32:35], v[128:131], v[198:201], v[32:35]
	v_mfma_f32_16x16x32_bf16 v[24:27], v[136:139], v[198:201], v[24:27]
	v_mfma_f32_16x16x32_bf16 v[16:19], v[128:131], v[206:209], v[16:19]
	v_mfma_f32_16x16x32_bf16 v[8:11], v[136:139], v[206:209], v[8:11]
	v_mfma_f32_16x16x32_bf16 v[60:63], v[132:135], v[180:183], v[60:63]
	v_mfma_f32_16x16x32_bf16 v[56:59], v[140:143], v[180:183], v[56:59]
	v_mfma_f32_16x16x32_bf16 v[48:51], v[132:135], v[188:191], v[48:51]
	v_mfma_f32_16x16x32_bf16 v[40:43], v[140:143], v[188:191], v[40:43]
	v_mfma_f32_16x16x32_bf16 v[32:35], v[132:135], v[202:205], v[32:35]
	v_mfma_f32_16x16x32_bf16 v[24:27], v[140:143], v[202:205], v[24:27]
	v_mfma_f32_16x16x32_bf16 v[16:19], v[132:135], v[210:213], v[16:19]
	v_mfma_f32_16x16x32_bf16 v[8:11], v[140:143], v[210:213], v[8:11]
	s_setprio 0
	s_setprio 1
	v_mfma_f32_16x16x32_bf16 v[52:55], v[144:147], v[160:163], v[52:55]
	v_mfma_f32_16x16x32_bf16 v[44:47], v[152:155], v[160:163], v[44:47]
	v_mfma_f32_16x16x32_bf16 v[36:39], v[144:147], v[184:187], v[36:39]
	v_mfma_f32_16x16x32_bf16 v[28:31], v[152:155], v[184:187], v[28:31]
	v_mfma_f32_16x16x32_bf16 v[20:23], v[144:147], v[198:201], v[20:23]
	v_mfma_f32_16x16x32_bf16 v[12:15], v[152:155], v[198:201], v[12:15]
	v_mfma_f32_16x16x32_bf16 v[4:7], v[144:147], v[206:209], v[4:7]
	v_mfma_f32_16x16x32_bf16 v[0:3], v[152:155], v[206:209], v[0:3]
	v_mfma_f32_16x16x32_bf16 v[52:55], v[148:151], v[180:183], v[52:55]
	v_mfma_f32_16x16x32_bf16 v[44:47], v[156:159], v[180:183], v[44:47]
	v_mfma_f32_16x16x32_bf16 v[36:39], v[148:151], v[188:191], v[36:39]
	v_mfma_f32_16x16x32_bf16 v[28:31], v[156:159], v[188:191], v[28:31]
	v_mfma_f32_16x16x32_bf16 v[20:23], v[148:151], v[202:205], v[20:23]
	v_mfma_f32_16x16x32_bf16 v[12:15], v[156:159], v[202:205], v[12:15]
	v_mfma_f32_16x16x32_bf16 v[4:7], v[148:151], v[210:213], v[4:7]
	v_mfma_f32_16x16x32_bf16 v[0:3], v[156:159], v[210:213], v[0:3]
	s_setprio 0
	s_barrier
	s_add_i32 s48, 0, 0x18000
	s_add_i32 s49, 0, 0x1c000
	s_add_u32 s18, s24, 0xb0000
	s_addc_u32 s19, s25, 0
	s_mov_b32 m0, s34
	v_lshl_add_u64 v[222:223], s[18:19], 0, v[164:165]
	global_load_lds_dwordx4 v[222:223], off
	v_lshl_add_u64 v[222:223], s[18:19], 0, v[168:169]
	s_mov_b32 m0, s35
	s_nop 0
	global_load_lds_dwordx4 v[222:223], off
	v_add_u32_e32 v140, s48, v193
	v_add_u32_e32 v156, s49, v193
	ds_read_b128 v[128:131], v140
	ds_read_b128 v[132:135], v140 offset:1024
	ds_read_b128 v[136:139], v140 offset:2048
	ds_read_b128 v[140:143], v140 offset:3072
	ds_read_b128 v[144:147], v156
	ds_read_b128 v[148:151], v156 offset:1024
	ds_read_b128 v[152:155], v156 offset:2048
	ds_read_b128 v[156:159], v156 offset:3072
	ds_read_b128 v[160:163], v197 offset:32768
	ds_read_b128 v[180:183], v197 offset:33792
	ds_read_b128 v[184:187], v197 offset:34816
	ds_read_b128 v[188:191], v197 offset:35840
	ds_read_b128 v[198:201], v197 offset:36864
	ds_read_b128 v[202:205], v197 offset:37888
	ds_read_b128 v[206:209], v197 offset:38912
	ds_read_b128 v[210:213], v197 offset:39936
	s_waitcnt vmcnt(8)
	s_waitcnt lgkmcnt(0)
	s_barrier
	s_setprio 1
	s_waitcnt lgkmcnt(0)
	v_mfma_f32_16x16x32_bf16 v[124:127], v[128:131], v[160:163], v[124:127]
	v_mfma_f32_16x16x32_bf16 v[120:123], v[136:139], v[160:163], v[120:123]
	v_mfma_f32_16x16x32_bf16 v[112:115], v[128:131], v[184:187], v[112:115]
	v_mfma_f32_16x16x32_bf16 v[104:107], v[136:139], v[184:187], v[104:107]
	v_mfma_f32_16x16x32_bf16 v[96:99], v[128:131], v[198:201], v[96:99]
	v_mfma_f32_16x16x32_bf16 v[88:91], v[136:139], v[198:201], v[88:91]
	v_mfma_f32_16x16x32_bf16 v[80:83], v[128:131], v[206:209], v[80:83]
	v_mfma_f32_16x16x32_bf16 v[72:75], v[136:139], v[206:209], v[72:75]
	v_mfma_f32_16x16x32_bf16 v[124:127], v[132:135], v[180:183], v[124:127]
	v_mfma_f32_16x16x32_bf16 v[120:123], v[140:143], v[180:183], v[120:123]
	v_mfma_f32_16x16x32_bf16 v[112:115], v[132:135], v[188:191], v[112:115]
	v_mfma_f32_16x16x32_bf16 v[104:107], v[140:143], v[188:191], v[104:107]
	v_mfma_f32_16x16x32_bf16 v[96:99], v[132:135], v[202:205], v[96:99]
	v_mfma_f32_16x16x32_bf16 v[88:91], v[140:143], v[202:205], v[88:91]
	v_mfma_f32_16x16x32_bf16 v[80:83], v[132:135], v[210:213], v[80:83]
	v_mfma_f32_16x16x32_bf16 v[72:75], v[140:143], v[210:213], v[72:75]
	s_setprio 0
	s_setprio 1
	v_mfma_f32_16x16x32_bf16 v[116:119], v[144:147], v[160:163], v[116:119]
	v_mfma_f32_16x16x32_bf16 v[108:111], v[152:155], v[160:163], v[108:111]
	v_mfma_f32_16x16x32_bf16 v[100:103], v[144:147], v[184:187], v[100:103]
	v_mfma_f32_16x16x32_bf16 v[92:95], v[152:155], v[184:187], v[92:95]
	v_mfma_f32_16x16x32_bf16 v[84:87], v[144:147], v[198:201], v[84:87]
	v_mfma_f32_16x16x32_bf16 v[76:79], v[152:155], v[198:201], v[76:79]
	v_mfma_f32_16x16x32_bf16 v[68:71], v[144:147], v[206:209], v[68:71]
	v_mfma_f32_16x16x32_bf16 v[64:67], v[152:155], v[206:209], v[64:67]
	v_mfma_f32_16x16x32_bf16 v[116:119], v[148:151], v[180:183], v[116:119]
	v_mfma_f32_16x16x32_bf16 v[108:111], v[156:159], v[180:183], v[108:111]
	v_mfma_f32_16x16x32_bf16 v[100:103], v[148:151], v[188:191], v[100:103]
	v_mfma_f32_16x16x32_bf16 v[92:95], v[156:159], v[188:191], v[92:95]
	v_mfma_f32_16x16x32_bf16 v[84:87], v[148:151], v[202:205], v[84:87]
	v_mfma_f32_16x16x32_bf16 v[76:79], v[156:159], v[202:205], v[76:79]
	v_mfma_f32_16x16x32_bf16 v[68:71], v[148:151], v[210:213], v[68:71]
	v_mfma_f32_16x16x32_bf16 v[64:67], v[156:159], v[210:213], v[64:67]
	s_setprio 0
	s_barrier
	s_add_i32 s18, s48, s28
	v_lshl_add_u64 v[214:215], v[214:215], 0, s[10:11]
	s_mov_b32 m0, s18
	s_nop 0
	global_load_lds_dwordx4 v[214:215], off
	s_add_i32 m0, s18, 0x2000
	s_add_u32 s18, s22, 0xb0080
	v_lshl_add_u64 v[214:215], v[216:217], 0, s[10:11]
	s_addc_u32 s19, s23, 0
	s_add_i32 s22, s49, s28
	global_load_lds_dwordx4 v[214:215], off
	v_lshl_add_u64 v[214:215], s[18:19], 0, v[166:167]
	s_mov_b32 m0, s22
	s_nop 0
	global_load_lds_dwordx4 v[214:215], off
	v_lshl_add_u64 v[214:215], s[18:19], 0, v[170:171]
	s_add_i32 m0, s22, 0x2000
	s_nop 0
	global_load_lds_dwordx4 v[214:215], off
	v_lshl_add_u64 v[214:215], v[218:219], 0, s[10:11]
	s_mov_b32 m0, s37
	s_nop 0
	global_load_lds_dwordx4 v[214:215], off
	v_lshl_add_u64 v[214:215], v[220:221], 0, s[10:11]
	s_mov_b32 m0, s38
	s_nop 0
	global_load_lds_dwordx4 v[214:215], off
	ds_read_b128 v[160:163], v197 offset:49152
	ds_read_b128 v[180:183], v197 offset:50176
	ds_read_b128 v[184:187], v197 offset:51200
	ds_read_b128 v[188:191], v197 offset:52224
	ds_read_b128 v[198:201], v197 offset:53248
	ds_read_b128 v[202:205], v197 offset:54272
	ds_read_b128 v[206:209], v197 offset:55296
	ds_read_b128 v[210:213], v197 offset:56320
	s_waitcnt vmcnt(8)
	s_waitcnt lgkmcnt(0)
	s_barrier
	s_setprio 1
	s_waitcnt lgkmcnt(0)
	v_mfma_f32_16x16x32_bf16 v[60:63], v[128:131], v[160:163], v[60:63]
	v_mfma_f32_16x16x32_bf16 v[56:59], v[136:139], v[160:163], v[56:59]
	v_mfma_f32_16x16x32_bf16 v[48:51], v[128:131], v[184:187], v[48:51]
	v_mfma_f32_16x16x32_bf16 v[40:43], v[136:139], v[184:187], v[40:43]
	v_mfma_f32_16x16x32_bf16 v[32:35], v[128:131], v[198:201], v[32:35]
	v_mfma_f32_16x16x32_bf16 v[24:27], v[136:139], v[198:201], v[24:27]
	v_mfma_f32_16x16x32_bf16 v[16:19], v[128:131], v[206:209], v[16:19]
	v_mfma_f32_16x16x32_bf16 v[8:11], v[136:139], v[206:209], v[8:11]
	v_mfma_f32_16x16x32_bf16 v[60:63], v[132:135], v[180:183], v[60:63]
	v_mfma_f32_16x16x32_bf16 v[56:59], v[140:143], v[180:183], v[56:59]
	v_mfma_f32_16x16x32_bf16 v[48:51], v[132:135], v[188:191], v[48:51]
	v_mfma_f32_16x16x32_bf16 v[40:43], v[140:143], v[188:191], v[40:43]
	v_mfma_f32_16x16x32_bf16 v[32:35], v[132:135], v[202:205], v[32:35]
	v_mfma_f32_16x16x32_bf16 v[24:27], v[140:143], v[202:205], v[24:27]
	v_mfma_f32_16x16x32_bf16 v[16:19], v[132:135], v[210:213], v[16:19]
	v_mfma_f32_16x16x32_bf16 v[8:11], v[140:143], v[210:213], v[8:11]
	s_setprio 0
	s_setprio 1
	v_mfma_f32_16x16x32_bf16 v[52:55], v[144:147], v[160:163], v[52:55]
	v_mfma_f32_16x16x32_bf16 v[44:47], v[152:155], v[160:163], v[44:47]
	v_mfma_f32_16x16x32_bf16 v[36:39], v[144:147], v[184:187], v[36:39]
	v_mfma_f32_16x16x32_bf16 v[28:31], v[152:155], v[184:187], v[28:31]
	v_mfma_f32_16x16x32_bf16 v[20:23], v[144:147], v[198:201], v[20:23]
	v_mfma_f32_16x16x32_bf16 v[12:15], v[152:155], v[198:201], v[12:15]
	v_mfma_f32_16x16x32_bf16 v[4:7], v[144:147], v[206:209], v[4:7]
	v_mfma_f32_16x16x32_bf16 v[0:3], v[152:155], v[206:209], v[0:3]
	v_mfma_f32_16x16x32_bf16 v[52:55], v[148:151], v[180:183], v[52:55]
	v_mfma_f32_16x16x32_bf16 v[44:47], v[156:159], v[180:183], v[44:47]
	v_mfma_f32_16x16x32_bf16 v[36:39], v[148:151], v[188:191], v[36:39]
	v_mfma_f32_16x16x32_bf16 v[28:31], v[156:159], v[188:191], v[28:31]
	v_mfma_f32_16x16x32_bf16 v[20:23], v[148:151], v[202:205], v[20:23]
	v_mfma_f32_16x16x32_bf16 v[12:15], v[156:159], v[202:205], v[12:15]
	v_mfma_f32_16x16x32_bf16 v[4:7], v[148:151], v[210:213], v[4:7]
	v_mfma_f32_16x16x32_bf16 v[0:3], v[156:159], v[210:213], v[0:3]
	s_setprio 0
	s_barrier
	s_add_i32 s47, s47, 2
	s_add_u32 s45, s45, 0x100
	s_addc_u32 s46, s46, 0
	s_cmp_gt_u32 s47, 41
	s_mov_b64 s[18:19], s[20:21]
	s_cbranch_scc0 .LBB0_687
	s_and_b64 vcc, exec, s[12:13]
	s_cbranch_vccz .LBB0_690
	s_barrier
